# P2 M-group order flip for MALL locality + P7 intra-XCD start stagger
# baseline (speedup 1.0000x reference)
.LBB0_362:
	s_add_i32 s2, s6, s2
	s_ashr_i32 s3, s2, 31
	s_lshr_b32 s3, s3, 26
	s_add_i32 s3, s2, s3
	s_ashr_i32 s5, s3, 6
	s_and_b32 s3, s3, 0xffc0
	s_sub_i32 s2, s2, s3
	s_bfe_i32 s3, s2, 0x80000
	s_bfe_u32 s3, s3, 0x3000c
	s_add_i32 s3, s2, s3
	s_bfe_i32 s6, s3, 0x80000
	s_and_b32 s3, s3, 0xf8
	s_sub_i32 s2, s2, s3
	s_lshl_b32 s5, s5, 3
	s_sext_i32_i16 s6, s6
	s_sext_i32_i8 s2, s2
	s_add_i32 s79, s5, s2
	s_xor_b32 s79, s79, 8
	s_ashr_i32 s80, s6, 3
	s_andn2_b64 vcc, exec, s[0:1]
	s_cbranch_vccnz .LBB0_357

.LBB0_373:
	s_ashr_i32 s10, s42, 3
	s_add_i32 s10, s54, s10
	s_ashr_i32 s11, s10, 31
	s_lshr_b32 s11, s11, 26
	s_add_i32 s11, s10, s11
	s_ashr_i32 s42, s11, 6
	s_lshl_b32 s42, s42, 3
	s_sub_i32 s43, 0x80, s42
	s_min_i32 s43, s43, 8
	s_abs_i32 s54, s43
	v_cvt_f32_u32_e32 v1, s54
	s_sub_i32 s77, 0, s54
	s_andn2_b32 s11, s11, 63
	s_sub_i32 s10, s10, s11
	v_rcp_iflag_f32_e32 v1, v1
	s_abs_i32 s11, s10
	s_xor_b32 s55, s10, s43
	s_ashr_i32 s55, s55, 31
	v_mul_f32_e32 v1, 0x4f7ffffe, v1
	v_cvt_u32_f32_e32 v1, v1
	s_nop 0
	v_readfirstlane_b32 s78, v1
	s_mul_i32 s77, s77, s78
	s_mul_hi_u32 s77, s78, s77
	s_add_i32 s78, s78, s77
	s_mul_hi_u32 s77, s11, s78
	s_mul_i32 s78, s77, s54
	s_sub_i32 s11, s11, s78
	s_add_i32 s81, s77, 1
	s_sub_i32 s78, s11, s54
	s_cmp_ge_u32 s11, s54
	s_cselect_b32 s77, s81, s77
	s_cselect_b32 s11, s78, s11
	s_add_i32 s78, s77, 1
	s_cmp_ge_u32 s11, s54
	s_cselect_b32 s11, s78, s77
	s_xor_b32 s11, s11, s55
	s_sub_i32 s77, s11, s55
	s_mul_i32 s11, s77, s43
	s_sub_i32 s10, s10, s11
	s_add_i32 s78, s42, s10
	s_xor_b32 s78, s78, 8

.LBB0_1307:
	s_cmp_lt_i32 s24, 8
	s_cselect_b64 s[0:1], -1, 0
	s_cmp_gt_i32 s25, 7
	s_cselect_b64 s[2:3], -1, 0
	s_and_b64 s[0:1], s[0:1], s[2:3]
	s_andn2_b64 vcc, exec, s[0:1]
	s_cbranch_vccnz .LBB0_1390
	s_bfe_u32 s32, s20, 0x30003
	s_cmp_eq_u32 s32, 0
	s_cbranch_scc1 .Lstg_p7_done
.Lstg_p7_loop:
	s_sleep 66
	s_sub_u32 s32, s32, 1
	s_cmp_lg_u32 s32, 0
	s_cbranch_scc1 .Lstg_p7_loop
.Lstg_p7_done:
	s_abs_i32 s0, s33
	v_cvt_f32_u32_e32 v1, s0
	s_sub_i32 s3, 0, s0
	s_abs_i32 s2, s20
	s_ashr_i32 s1, s20, 31
	v_rcp_iflag_f32_e32 v1, v1
	s_waitcnt vmcnt(0) lgkmcnt(0)
	s_barrier
	v_mul_f32_e32 v1, 0x4f7ffffe, v1
	v_cvt_u32_f32_e32 v1, v1
	s_nop 0
	v_readfirstlane_b32 s4, v1
	s_mul_i32 s3, s3, s4
	s_mul_hi_u32 s3, s4, s3
	s_add_i32 s4, s4, s3
	s_mul_hi_u32 s3, s2, s4
	s_mul_i32 s3, s3, s0
	s_sub_i32 s2, s2, s3
	s_sub_i32 s3, s2, s0
	s_cmp_ge_u32 s2, s0
	s_cselect_b32 s2, s3, s2
	s_sub_i32 s3, s2, s0
	s_cmp_ge_u32 s2, s0
	s_cselect_b32 s0, s3, s2
	s_xor_b32 s0, s0, s1
	s_sub_i32 s18, s0, s1
	s_cmpk_gt_i32 s18, 0x3ff
	v_readfirstlane_b32 s3, v0
	s_cbranch_scc1 .LBB0_1336
	s_ashr_i32 s19, s18, 31
	s_lshr_b32 s0, s19, 29
	s_add_i32 s5, s18, s0
	s_and_b32 s0, s5, -8
	s_sub_i32 s4, s18, s0
	s_cmp_gt_i32 s4, -1
	s_cbranch_scc0 .LBB0_1311
	s_lshl_b32 s2, s4, 7
	s_ashr_i32 s0, s5, 3
	s_cbranch_execz .LBB0_1312
	s_branch .LBB0_1313
